# PH5 loop: row-offset v_mad_u32_u24 computed only in the first and last K iteration of a unit (persistent registers) instead of every iteration; on top of v83
# speedup vs baseline: 1.0001x; 1.0001x over previous
; #define PG8_STAGE(bufoff, gbase, RR, ld) do { _Pragma("unroll") for (int _i = 0; _i < 2; ++_i) \
;         __builtin_amdgcn_global_load_lds((const unsigned*)((const char*)(gbase) + (RR)[_i] * (ld) + C2[_i]), (LAS unsigned*)(lds + (bufoff) + ldsw + _i * 8192), 16, 0, 0); } while (0)
; #define PG8_LDA(dst, b, h) do { _Pragma("unroll") for (int m = 0; m < 4; ++m) _Pragma("unroll") for (int k = 0; k < 2; ++k) dst[m][k] = *(const LAS bf16x8*)(lds + PG8_SA(b, h) + aoff + m * 2048 + k * 1024); } while (0)
; #define PG8_LDB(dst, b, h) do { _Pragma("unroll") for (int n = 0; n < 2; ++n) _Pragma("unroll") for (int k = 0; k < 2; ++k) dst[n][k] = *(const LAS bf16x8*)(lds + PG8_SB(b, h) + boff + n * 2048 + k * 1024); } while (0)
; #define PG8_WAIT_V(n) asm volatile("s_waitcnt vmcnt(" #n ")" ::: "memory")
; #define PG8_WAIT_L(n) asm volatile("s_waitcnt lgkmcnt(" #n ")" ::: "memory")
; #define PG8_BAR __builtin_amdgcn_s_barrier()
; #define PG8_SCHED __builtin_amdgcn_sched_barrier(0)
; template <class Sched, class Epi>
; __device__ __forceinline__ void gemm_run(LAS unsigned char* lds, const Sched& S, const Epi& E) {
;     ...
;     for (;;) {
;         const bool has_next = S.next(ui + 1, nxt);
;         const char* nA = has_next ? nxt.A : cA; const char* nB = has_next ? nxt.B : cB; const unsigned nlda = has_next ? nxt.lda : lda, nldb = has_next ? nxt.ldb : ldb;
;         const int nt = cur.nt;
;         for (int t = 0; t < nt; t += 2) {
;             const bool last = (t == nt - 2);
;             const char* a1 = cA + (size_t)(t + 1) * kstep;
;             const char* a2 = last ? nA : cA + (size_t)(t + 2) * kstep; const char* b2 = last ? nB : cB + (size_t)(t + 2) * kstep;
;             const unsigned la2 = last ? nlda : lda, lb2 = last ? nldb : ldb;
;             const char* a3 = a2 + kstep; const char* b3 = b2 + kstep;
;             PG8_LDB(B0, 0, 0); PG8_LDB(B1, 0, 1); PG8_SCHED; PG8_LDA(At, 0, 0); PG8_STAGE(PG8_SA(1, 1), a1 + (size_t)HALF * lda, RA, lda);
;             PG8_WAIT_V(8); PG8_WAIT_L(0); PG8_BAR; PG8_MMA(0, 0, At, B0); PG8_MMA(0, 1, At, B1); PG8_BAR; PG8_SCHED;
;             PG8_LDA(At, 0, 1); PG8_STAGE(PG8_SB(0, 0), b2, RB, lb2); PG8_STAGE(PG8_SB(0, 1), b2 + (size_t)HALF * lb2, RB, lb2); PG8_STAGE(PG8_SA(0, 0), a2, RA, la2);
;             PG8_WAIT_V(8); PG8_WAIT_L(0); PG8_BAR; PG8_MMA(1, 0, At, B0); PG8_MMA(1, 1, At, B1); PG8_BAR; PG8_SCHED;
.LBB0_805:
	s_mov_b32 s57, s7
	s_lshl_b64 s[48:49], s[56:57], 7
	v_mad_u32_u24 v224, v191, s56, v150
	v_mad_u32_u24 v226, v192, s56, v150
	v_add_u32_e32 v224, s48, v224
	v_add_u32_e32 v226, s48, v226
	v_mul_lo_u32 v148, v191, s56
	v_lshl_add_u64 v[2:3], s[54:55], 0, v[150:151]
	v_lshl_add_u64 v[4:5], s[48:49], 0, v[148:149]
	v_mul_lo_u32 v148, v192, s56
	s_add_i32 s44, s81, -2
	v_lshl_add_u64 v[130:131], v[2:3], 0, v[4:5]
	v_lshl_add_u64 v[4:5], s[48:49], 0, v[148:149]
	s_add_u32 s45, s58, 0x100
	v_lshl_add_u64 v[132:133], v[2:3], 0, v[4:5]
	s_addc_u32 s46, s59, 0
	s_mov_b32 s6, 0
	s_mov_b64 s[58:59], 0
	ds_read_b128 v[134:137], v193
	ds_read_b128 v[138:141], v193 offset:1024
	ds_read_b128 v[142:145], v193 offset:2048
	ds_read_b128 v[152:155], v193 offset:3072
	ds_read_b128 v[156:159], v194
	ds_read_b128 v[160:163], v194 offset:1024
	ds_read_b128 v[164:167], v194 offset:2048
	ds_read_b128 v[168:171], v194 offset:3072
	s_add_i32 s47, s6, 2
	s_add_u32 s48, s54, s58
	s_addc_u32 s49, s55, s59
	s_mov_b32 s98, s48
	s_mov_b32 s99, s49
	s_add_u32 s48, s48, 0x100
	s_addc_u32 s49, s49, 0
	s_add_u32 s50, s45, s58
	s_addc_u32 s51, s46, s59
	s_cmp_eq_u32 s44, s6
	s_cselect_b32 s6, s39, s82
	s_cselect_b32 s61, s31, s49
	s_cselect_b32 s60, s30, s48
	s_cselect_b32 s62, s80, s56
	s_cselect_b32 s49, s41, s51
	s_cselect_b32 s48, s40, s50
	v_mad_u32_u24 v216, v185, s6, v146
	v_mad_u32_u24 v218, v187, s6, v146
	v_mad_u32_u24 v220, v184, s62, v146
	v_mad_u32_u24 v222, v186, s62, v146
	s_add_i32 m0, s43, 0xc000
	ds_read_b128 v[172:175], v195
	ds_read_b128 v[176:179], v195 offset:1024
	ds_read_b128 v[180:183], v195 offset:2048
	ds_read_b128 v[196:199], v195 offset:3072
	ds_read_b128 v[200:203], v195 offset:4096
	ds_read_b128 v[204:207], v195 offset:5120
	ds_read_b128 v[208:211], v195 offset:6144
	ds_read_b128 v[212:215], v195 offset:7168
	global_load_lds_dwordx4 v224, s[98:99]
	s_add_i32 m0, s43, 0xe000
	s_nop 0
	global_load_lds_dwordx4 v226, s[98:99]
	s_waitcnt vmcnt(8)
	s_waitcnt lgkmcnt(0)
	s_barrier
	s_waitcnt lgkmcnt(0)
	v_mfma_f32_16x16x32_bf16 v[126:129], v[134:137], v[172:175], 0
	v_mfma_f32_16x16x32_bf16 v[118:121], v[142:145], v[172:175], 0
	v_mfma_f32_16x16x32_bf16 v[110:113], v[134:137], v[180:183], 0
	v_mfma_f32_16x16x32_bf16 v[102:105], v[142:145], v[180:183], 0
	v_mfma_f32_16x16x32_bf16 v[94:97], v[134:137], v[200:203], 0
	v_mfma_f32_16x16x32_bf16 v[86:89], v[142:145], v[200:203], 0
	v_mfma_f32_16x16x32_bf16 v[78:81], v[134:137], v[208:211], 0
	v_mfma_f32_16x16x32_bf16 v[70:73], v[142:145], v[208:211], 0
	v_mfma_f32_16x16x32_bf16 v[126:129], v[138:141], v[176:179], v[126:129]
	v_mfma_f32_16x16x32_bf16 v[118:121], v[152:155], v[176:179], v[118:121]
	v_mfma_f32_16x16x32_bf16 v[110:113], v[138:141], v[196:199], v[110:113]
	v_mfma_f32_16x16x32_bf16 v[102:105], v[152:155], v[196:199], v[102:105]
	v_mfma_f32_16x16x32_bf16 v[94:97], v[138:141], v[204:207], v[94:97]
	v_mfma_f32_16x16x32_bf16 v[86:89], v[152:155], v[204:207], v[86:89]
	v_mfma_f32_16x16x32_bf16 v[78:81], v[138:141], v[212:215], v[78:81]
	v_mfma_f32_16x16x32_bf16 v[70:73], v[152:155], v[212:215], v[70:73]
	v_mfma_f32_16x16x32_bf16 v[122:125], v[156:159], v[172:175], 0
	v_mfma_f32_16x16x32_bf16 v[114:117], v[164:167], v[172:175], 0
	v_mfma_f32_16x16x32_bf16 v[106:109], v[156:159], v[180:183], 0
	v_mfma_f32_16x16x32_bf16 v[98:101], v[164:167], v[180:183], 0
	v_mfma_f32_16x16x32_bf16 v[90:93], v[156:159], v[200:203], 0
	v_mfma_f32_16x16x32_bf16 v[82:85], v[164:167], v[200:203], 0
	v_mfma_f32_16x16x32_bf16 v[74:77], v[156:159], v[208:211], 0
	v_mfma_f32_16x16x32_bf16 v[66:69], v[164:167], v[208:211], 0
	v_mfma_f32_16x16x32_bf16 v[122:125], v[160:163], v[176:179], v[122:125]
	v_mfma_f32_16x16x32_bf16 v[114:117], v[168:171], v[176:179], v[114:117]
	v_mfma_f32_16x16x32_bf16 v[106:109], v[160:163], v[196:199], v[106:109]
	v_mfma_f32_16x16x32_bf16 v[98:101], v[168:171], v[196:199], v[98:101]
	v_mfma_f32_16x16x32_bf16 v[90:93], v[160:163], v[204:207], v[90:93]
	v_mfma_f32_16x16x32_bf16 v[82:85], v[168:171], v[204:207], v[82:85]
	v_mfma_f32_16x16x32_bf16 v[74:77], v[160:163], v[212:215], v[74:77]
	v_mfma_f32_16x16x32_bf16 v[66:69], v[168:171], v[212:215], v[66:69]
	s_barrier
	s_add_i32 s50, s74, s3
	s_mov_b32 m0, s50
	ds_read_b128 v[172:175], v195 offset:16384
	ds_read_b128 v[176:179], v195 offset:17408
	ds_read_b128 v[180:183], v195 offset:18432
	ds_read_b128 v[196:199], v195 offset:19456
	ds_read_b128 v[200:203], v195 offset:20480
	ds_read_b128 v[204:207], v195 offset:21504
	ds_read_b128 v[208:211], v195 offset:22528
	ds_read_b128 v[212:215], v195 offset:23552
	global_load_lds_dwordx4 v216, s[48:49]
	s_add_i32 m0, s50, 0x2000
	s_lshl_b64 s[50:51], s[6:7], 7
	s_mov_b64 s[98:99], s[48:49]
	s_add_u32 s48, s48, s50
	s_addc_u32 s49, s49, s51
	s_mov_b64 s[100:101], s[48:49]
	s_add_i32 s6, s75, s3
	global_load_lds_dwordx4 v218, s[98:99]
	s_mov_b32 m0, s6
	global_load_lds_dwordx4 v216, s[48:49]
	s_add_i32 m0, s6, 0x2000
	global_load_lds_dwordx4 v218, s[48:49]
	s_mov_b32 m0, s43
	s_nop 0
	global_load_lds_dwordx4 v220, s[60:61]
	s_mov_b32 m0, s65
	s_nop 0
	global_load_lds_dwordx4 v222, s[60:61]
	s_waitcnt vmcnt(8)
	s_waitcnt lgkmcnt(0)
	s_barrier
; #define PG8_STAGE(bufoff, gbase, RR, ld) do { _Pragma("unroll") for (int _i = 0; _i < 2; ++_i) \
;         __builtin_amdgcn_global_load_lds((const unsigned*)((const char*)(gbase) + (RR)[_i] * (ld) + C2[_i]), (LAS unsigned*)(lds + (bufoff) + ldsw + _i * 8192), 16, 0, 0); } while (0)
; #define PG8_LDA(dst, b, h) do { _Pragma("unroll") for (int m = 0; m < 4; ++m) _Pragma("unroll") for (int k = 0; k < 2; ++k) dst[m][k] = *(const LAS bf16x8*)(lds + PG8_SA(b, h) + aoff + m * 2048 + k * 1024); } while (0)
; #define PG8_LDB(dst, b, h) do { _Pragma("unroll") for (int n = 0; n < 2; ++n) _Pragma("unroll") for (int k = 0; k < 2; ++k) dst[n][k] = *(const LAS bf16x8*)(lds + PG8_SB(b, h) + boff + n * 2048 + k * 1024); } while (0)
; #define PG8_MMA(ai, bj, At, Bt) do { __builtin_amdgcn_s_setprio(1); _Pragma("unroll") for (int m = 0; m < 4; ++m) _Pragma("unroll") for (int n = 0; n < 2; ++n) _Pragma("unroll") for (int k = 0; k < 2; ++k) \
;         acc[ai][bj][m][n] = __builtin_amdgcn_mfma_f32_16x16x32_bf16(Bt[n][k], At[m][k], acc[ai][bj][m][n], 0, 0, 0); __builtin_amdgcn_s_setprio(0); } while (0)
; #define PG8_WAIT_V(n) asm volatile("s_waitcnt vmcnt(" #n ")" ::: "memory")
; #define PG8_WAIT_L(n) asm volatile("s_waitcnt lgkmcnt(" #n ")" ::: "memory")
; #define PG8_BAR __builtin_amdgcn_s_barrier()
; #define PG8_SCHED __builtin_amdgcn_sched_barrier(0)
; template <class Sched, class Epi>
; __device__ __forceinline__ void gemm_run(LAS unsigned char* lds, const Sched& S, const Epi& E) {
;     ...
;             PG8_WAIT_V(8); PG8_WAIT_L(0); PG8_BAR; PG8_MMA(1, 0, At, B0); PG8_MMA(1, 1, At, B1); PG8_BAR; PG8_SCHED;
;             PG8_LDB(B0, 1, 0); PG8_LDB(B1, 1, 1); PG8_SCHED; PG8_LDA(At, 1, 0); PG8_STAGE(PG8_SA(0, 1), a2 + (size_t)HALF * la2, RA, la2);
;             PG8_WAIT_V(8); PG8_WAIT_L(0); PG8_BAR; PG8_MMA(0, 0, At, B0); PG8_MMA(0, 1, At, B1); PG8_BAR; PG8_SCHED;
	s_waitcnt lgkmcnt(0)
	v_mfma_f32_16x16x32_bf16 v[62:65], v[134:137], v[172:175], 0
	v_mfma_f32_16x16x32_bf16 v[54:57], v[142:145], v[172:175], 0
	v_mfma_f32_16x16x32_bf16 v[46:49], v[134:137], v[180:183], 0
	v_mfma_f32_16x16x32_bf16 v[38:41], v[142:145], v[180:183], 0
	v_mfma_f32_16x16x32_bf16 v[30:33], v[134:137], v[200:203], 0
	v_mfma_f32_16x16x32_bf16 v[22:25], v[142:145], v[200:203], 0
	v_mfma_f32_16x16x32_bf16 v[14:17], v[134:137], v[208:211], 0
	v_mfma_f32_16x16x32_bf16 v[6:9], v[142:145], v[208:211], 0
	v_mfma_f32_16x16x32_bf16 v[62:65], v[138:141], v[176:179], v[62:65]
	v_mfma_f32_16x16x32_bf16 v[54:57], v[152:155], v[176:179], v[54:57]
	v_mfma_f32_16x16x32_bf16 v[46:49], v[138:141], v[196:199], v[46:49]
	v_mfma_f32_16x16x32_bf16 v[38:41], v[152:155], v[196:199], v[38:41]
	v_mfma_f32_16x16x32_bf16 v[30:33], v[138:141], v[204:207], v[30:33]
	v_mfma_f32_16x16x32_bf16 v[22:25], v[152:155], v[204:207], v[22:25]
	v_mfma_f32_16x16x32_bf16 v[14:17], v[138:141], v[212:215], v[14:17]
	v_mfma_f32_16x16x32_bf16 v[6:9], v[152:155], v[212:215], v[6:9]
	v_mfma_f32_16x16x32_bf16 v[58:61], v[156:159], v[172:175], 0
	v_mfma_f32_16x16x32_bf16 v[50:53], v[164:167], v[172:175], 0
	v_mfma_f32_16x16x32_bf16 v[42:45], v[156:159], v[180:183], 0
	v_mfma_f32_16x16x32_bf16 v[34:37], v[164:167], v[180:183], 0
	v_mfma_f32_16x16x32_bf16 v[26:29], v[156:159], v[200:203], 0
	v_mfma_f32_16x16x32_bf16 v[18:21], v[164:167], v[200:203], 0
	v_mfma_f32_16x16x32_bf16 v[10:13], v[156:159], v[208:211], 0
	v_mfma_f32_16x16x32_bf16 v[2:5], v[164:167], v[208:211], 0
	v_mfma_f32_16x16x32_bf16 v[58:61], v[160:163], v[176:179], v[58:61]
	v_mfma_f32_16x16x32_bf16 v[50:53], v[168:171], v[176:179], v[50:53]
	v_mfma_f32_16x16x32_bf16 v[42:45], v[160:163], v[196:199], v[42:45]
	v_mfma_f32_16x16x32_bf16 v[34:37], v[168:171], v[196:199], v[34:37]
	v_mfma_f32_16x16x32_bf16 v[26:29], v[160:163], v[204:207], v[26:29]
	v_mfma_f32_16x16x32_bf16 v[18:21], v[168:171], v[204:207], v[18:21]
	v_mfma_f32_16x16x32_bf16 v[10:13], v[160:163], v[212:215], v[10:13]
	v_mfma_f32_16x16x32_bf16 v[2:5], v[168:171], v[212:215], v[2:5]
	s_barrier
	s_add_i32 s6, 0, 0x18000
	s_add_i32 s50, 0, 0x1c000
	ds_read_b128 v[134:137], v193 offset:32768
	ds_read_b128 v[138:141], v193 offset:33792
	ds_read_b128 v[142:145], v193 offset:34816
	ds_read_b128 v[152:155], v193 offset:35840
	ds_read_b128 v[156:159], v194 offset:32768
	ds_read_b128 v[160:163], v194 offset:33792
	ds_read_b128 v[164:167], v194 offset:34816
	ds_read_b128 v[168:171], v194 offset:35840
	s_mov_b32 s63, s7
	s_lshl_b64 s[48:49], s[62:63], 7
	s_add_u32 s48, s60, s48
	s_addc_u32 s49, s61, s49
	s_mov_b32 m0, s66
	ds_read_b128 v[172:175], v195 offset:32768
	ds_read_b128 v[176:179], v195 offset:33792
	ds_read_b128 v[180:183], v195 offset:34816
	ds_read_b128 v[196:199], v195 offset:35840
	ds_read_b128 v[200:203], v195 offset:36864
	ds_read_b128 v[204:207], v195 offset:37888
	ds_read_b128 v[208:211], v195 offset:38912
	ds_read_b128 v[212:215], v195 offset:39936
	global_load_lds_dwordx4 v220, s[48:49]
	s_mov_b32 m0, s67
	s_nop 0
	global_load_lds_dwordx4 v222, s[48:49]
	s_waitcnt vmcnt(8)
	s_waitcnt lgkmcnt(0)
	s_barrier
	s_waitcnt lgkmcnt(0)
	v_mfma_f32_16x16x32_bf16 v[126:129], v[134:137], v[172:175], v[126:129]
	v_mfma_f32_16x16x32_bf16 v[118:121], v[142:145], v[172:175], v[118:121]
	v_mfma_f32_16x16x32_bf16 v[110:113], v[134:137], v[180:183], v[110:113]
	v_mfma_f32_16x16x32_bf16 v[102:105], v[142:145], v[180:183], v[102:105]
	v_mfma_f32_16x16x32_bf16 v[94:97], v[134:137], v[200:203], v[94:97]
	v_mfma_f32_16x16x32_bf16 v[86:89], v[142:145], v[200:203], v[86:89]
	v_mfma_f32_16x16x32_bf16 v[78:81], v[134:137], v[208:211], v[78:81]
	v_mfma_f32_16x16x32_bf16 v[70:73], v[142:145], v[208:211], v[70:73]
	v_mfma_f32_16x16x32_bf16 v[126:129], v[138:141], v[176:179], v[126:129]
	v_mfma_f32_16x16x32_bf16 v[118:121], v[152:155], v[176:179], v[118:121]
	v_mfma_f32_16x16x32_bf16 v[110:113], v[138:141], v[196:199], v[110:113]
	v_mfma_f32_16x16x32_bf16 v[102:105], v[152:155], v[196:199], v[102:105]
	v_mfma_f32_16x16x32_bf16 v[94:97], v[138:141], v[204:207], v[94:97]
	v_mfma_f32_16x16x32_bf16 v[86:89], v[152:155], v[204:207], v[86:89]
	v_mfma_f32_16x16x32_bf16 v[78:81], v[138:141], v[212:215], v[78:81]
	v_mfma_f32_16x16x32_bf16 v[70:73], v[152:155], v[212:215], v[70:73]
	v_mfma_f32_16x16x32_bf16 v[122:125], v[156:159], v[172:175], v[122:125]
	v_mfma_f32_16x16x32_bf16 v[114:117], v[164:167], v[172:175], v[114:117]
	v_mfma_f32_16x16x32_bf16 v[106:109], v[156:159], v[180:183], v[106:109]
	v_mfma_f32_16x16x32_bf16 v[98:101], v[164:167], v[180:183], v[98:101]
	v_mfma_f32_16x16x32_bf16 v[90:93], v[156:159], v[200:203], v[90:93]
	v_mfma_f32_16x16x32_bf16 v[82:85], v[164:167], v[200:203], v[82:85]
	v_mfma_f32_16x16x32_bf16 v[74:77], v[156:159], v[208:211], v[74:77]
	v_mfma_f32_16x16x32_bf16 v[66:69], v[164:167], v[208:211], v[66:69]
	v_mfma_f32_16x16x32_bf16 v[122:125], v[160:163], v[176:179], v[122:125]
	v_mfma_f32_16x16x32_bf16 v[114:117], v[168:171], v[176:179], v[114:117]
	v_mfma_f32_16x16x32_bf16 v[106:109], v[160:163], v[196:199], v[106:109]
	v_mfma_f32_16x16x32_bf16 v[98:101], v[168:171], v[196:199], v[98:101]
	v_mfma_f32_16x16x32_bf16 v[90:93], v[160:163], v[204:207], v[90:93]
	v_mfma_f32_16x16x32_bf16 v[82:85], v[168:171], v[204:207], v[82:85]
	v_mfma_f32_16x16x32_bf16 v[74:77], v[160:163], v[212:215], v[74:77]
	v_mfma_f32_16x16x32_bf16 v[66:69], v[168:171], v[212:215], v[66:69]
	s_barrier
; #define PG8_STAGE(bufoff, gbase, RR, ld) do { _Pragma("unroll") for (int _i = 0; _i < 2; ++_i) \
;         __builtin_amdgcn_global_load_lds((const unsigned*)((const char*)(gbase) + (RR)[_i] * (ld) + C2[_i]), (LAS unsigned*)(lds + (bufoff) + ldsw + _i * 8192), 16, 0, 0); } while (0)
; #define PG8_LDA(dst, b, h) do { _Pragma("unroll") for (int m = 0; m < 4; ++m) _Pragma("unroll") for (int k = 0; k < 2; ++k) dst[m][k] = *(const LAS bf16x8*)(lds + PG8_SA(b, h) + aoff + m * 2048 + k * 1024); } while (0)
; #define PG8_LDB(dst, b, h) do { _Pragma("unroll") for (int n = 0; n < 2; ++n) _Pragma("unroll") for (int k = 0; k < 2; ++k) dst[n][k] = *(const LAS bf16x8*)(lds + PG8_SB(b, h) + boff + n * 2048 + k * 1024); } while (0)
; #define PG8_MMA(ai, bj, At, Bt) do { __builtin_amdgcn_s_setprio(1); _Pragma("unroll") for (int m = 0; m < 4; ++m) _Pragma("unroll") for (int n = 0; n < 2; ++n) _Pragma("unroll") for (int k = 0; k < 2; ++k) \
;         acc[ai][bj][m][n] = __builtin_amdgcn_mfma_f32_16x16x32_bf16(Bt[n][k], At[m][k], acc[ai][bj][m][n], 0, 0, 0); __builtin_amdgcn_s_setprio(0); } while (0)
; #define PG8_WAIT_V(n) asm volatile("s_waitcnt vmcnt(" #n ")" ::: "memory")
; #define PG8_WAIT_L(n) asm volatile("s_waitcnt lgkmcnt(" #n ")" ::: "memory")
; #define PG8_BAR __builtin_amdgcn_s_barrier()
; #define PG8_SCHED __builtin_amdgcn_sched_barrier(0)
; template <class Sched, class Epi>
; __device__ __forceinline__ void gemm_run(LAS unsigned char* lds, const Sched& S, const Epi& E) {
;     ...
;         for (int t = 0; t < nt; t += 2) {
;             const bool last = (t == nt - 2);
;             const char* a1 = cA + (size_t)(t + 1) * kstep;
;             const char* a2 = last ? nA : cA + (size_t)(t + 2) * kstep; const char* b2 = last ? nB : cB + (size_t)(t + 2) * kstep;
;             const unsigned la2 = last ? nlda : lda, lb2 = last ? nldb : ldb;
;             const char* a3 = a2 + kstep; const char* b3 = b2 + kstep;
;             PG8_LDB(B0, 0, 0); PG8_LDB(B1, 0, 1); PG8_SCHED; PG8_LDA(At, 0, 0); PG8_STAGE(PG8_SA(1, 1), a1 + (size_t)HALF * lda, RA, lda);
;     ...
;             PG8_LDA(At, 1, 1); PG8_STAGE(PG8_SB(1, 0), b3, RB, lb2); PG8_STAGE(PG8_SB(1, 1), b3 + (size_t)HALF * lb2, RB, lb2); PG8_STAGE(PG8_SA(1, 0), a3, RA, la2);
;             PG8_WAIT_V(8); PG8_WAIT_L(0); PG8_BAR; PG8_MMA(1, 0, At, B0); PG8_MMA(1, 1, At, B1); PG8_BAR; PG8_SCHED;
	s_add_i32 s6, s6, s3
	s_add_u32 s98, s98, 0x80
	s_addc_u32 s99, s99, 0
	s_mov_b32 m0, s6
	ds_read_b128 v[172:175], v195 offset:49152
	ds_read_b128 v[176:179], v195 offset:50176
	ds_read_b128 v[180:183], v195 offset:51200
	ds_read_b128 v[196:199], v195 offset:52224
	ds_read_b128 v[200:203], v195 offset:53248
	ds_read_b128 v[204:207], v195 offset:54272
	ds_read_b128 v[208:211], v195 offset:55296
	ds_read_b128 v[212:215], v195 offset:56320
	global_load_lds_dwordx4 v216, s[98:99]
	s_add_i32 m0, s6, 0x2000
	s_add_i32 s6, s50, s3
	global_load_lds_dwordx4 v218, s[98:99]
	s_add_u32 s100, s100, 0x80
	s_addc_u32 s101, s101, 0
	s_mov_b32 m0, s6
	s_nop 0
	global_load_lds_dwordx4 v216, s[100:101]
	s_add_i32 m0, s6, 0x2000
	s_nop 0
	global_load_lds_dwordx4 v218, s[100:101]
	s_add_u32 s48, s60, 0x80
	s_addc_u32 s49, s61, 0
	s_mov_b32 m0, s68
	s_nop 0
	global_load_lds_dwordx4 v220, s[48:49]
	s_mov_b32 m0, s69
	s_nop 0
	global_load_lds_dwordx4 v222, s[48:49]
	s_waitcnt vmcnt(8)
	s_waitcnt lgkmcnt(0)
	s_barrier
	s_waitcnt lgkmcnt(0)
	v_mfma_f32_16x16x32_bf16 v[62:65], v[134:137], v[172:175], v[62:65]
	v_mfma_f32_16x16x32_bf16 v[54:57], v[142:145], v[172:175], v[54:57]
	v_mfma_f32_16x16x32_bf16 v[46:49], v[134:137], v[180:183], v[46:49]
	v_mfma_f32_16x16x32_bf16 v[38:41], v[142:145], v[180:183], v[38:41]
	v_mfma_f32_16x16x32_bf16 v[30:33], v[134:137], v[200:203], v[30:33]
	v_mfma_f32_16x16x32_bf16 v[22:25], v[142:145], v[200:203], v[22:25]
	v_mfma_f32_16x16x32_bf16 v[14:17], v[134:137], v[208:211], v[14:17]
	v_mfma_f32_16x16x32_bf16 v[6:9], v[142:145], v[208:211], v[6:9]
	v_mfma_f32_16x16x32_bf16 v[62:65], v[138:141], v[176:179], v[62:65]
	v_mfma_f32_16x16x32_bf16 v[54:57], v[152:155], v[176:179], v[54:57]
	v_mfma_f32_16x16x32_bf16 v[46:49], v[138:141], v[196:199], v[46:49]
	v_mfma_f32_16x16x32_bf16 v[38:41], v[152:155], v[196:199], v[38:41]
	v_mfma_f32_16x16x32_bf16 v[30:33], v[138:141], v[204:207], v[30:33]
	v_mfma_f32_16x16x32_bf16 v[22:25], v[152:155], v[204:207], v[22:25]
	v_mfma_f32_16x16x32_bf16 v[14:17], v[138:141], v[212:215], v[14:17]
	v_mfma_f32_16x16x32_bf16 v[6:9], v[152:155], v[212:215], v[6:9]
	v_mfma_f32_16x16x32_bf16 v[58:61], v[156:159], v[172:175], v[58:61]
	v_mfma_f32_16x16x32_bf16 v[50:53], v[164:167], v[172:175], v[50:53]
	v_mfma_f32_16x16x32_bf16 v[42:45], v[156:159], v[180:183], v[42:45]
	v_mfma_f32_16x16x32_bf16 v[34:37], v[164:167], v[180:183], v[34:37]
	v_mfma_f32_16x16x32_bf16 v[26:29], v[156:159], v[200:203], v[26:29]
	v_mfma_f32_16x16x32_bf16 v[18:21], v[164:167], v[200:203], v[18:21]
	v_mfma_f32_16x16x32_bf16 v[10:13], v[156:159], v[208:211], v[10:13]
	v_mfma_f32_16x16x32_bf16 v[2:5], v[164:167], v[208:211], v[2:5]
	v_mfma_f32_16x16x32_bf16 v[58:61], v[160:163], v[176:179], v[58:61]
	v_mfma_f32_16x16x32_bf16 v[50:53], v[168:171], v[176:179], v[50:53]
	v_mfma_f32_16x16x32_bf16 v[42:45], v[160:163], v[196:199], v[42:45]
	v_mfma_f32_16x16x32_bf16 v[34:37], v[168:171], v[196:199], v[34:37]
	v_mfma_f32_16x16x32_bf16 v[26:29], v[160:163], v[204:207], v[26:29]
	v_mfma_f32_16x16x32_bf16 v[18:21], v[168:171], v[204:207], v[18:21]
	v_mfma_f32_16x16x32_bf16 v[10:13], v[160:163], v[212:215], v[10:13]
	v_mfma_f32_16x16x32_bf16 v[2:5], v[168:171], v[212:215], v[2:5]
	s_barrier
	s_add_u32 s58, s58, 0x100
	s_addc_u32 s59, s59, 0
	s_cmp_ge_i32 s47, s81
	s_mov_b32 s6, s47
	s_cbranch_scc0 .LBB0_806
	.p2align 6
.LBB0_806:
	ds_read_b128 v[134:137], v193
	ds_read_b128 v[138:141], v193 offset:1024
	ds_read_b128 v[142:145], v193 offset:2048
	ds_read_b128 v[152:155], v193 offset:3072
	ds_read_b128 v[156:159], v194
	ds_read_b128 v[160:163], v194 offset:1024
	ds_read_b128 v[164:167], v194 offset:2048
	ds_read_b128 v[168:171], v194 offset:3072
	s_add_i32 s47, s6, 2
	s_add_u32 s48, s54, s58
	s_addc_u32 s49, s55, s59
	s_mov_b32 s98, s48
	s_mov_b32 s99, s49
	s_add_u32 s48, s48, 0x100
	s_addc_u32 s49, s49, 0
	s_add_u32 s50, s45, s58
	s_addc_u32 s51, s46, s59
	s_cmp_eq_u32 s44, s6
	s_cselect_b32 s6, s39, s82
	s_cselect_b32 s61, s31, s49
	s_cselect_b32 s60, s30, s48
	s_cselect_b32 s62, s80, s56
	s_cselect_b32 s49, s41, s51
	s_cselect_b32 s48, s40, s50
	s_cbranch_scc0 .Lmad806_skip
	v_mad_u32_u24 v216, v185, s6, v146
	v_mad_u32_u24 v218, v187, s6, v146
	v_mad_u32_u24 v220, v184, s62, v146
	v_mad_u32_u24 v222, v186, s62, v146
; #define PG8_STAGE(bufoff, gbase, RR, ld) do { _Pragma("unroll") for (int _i = 0; _i < 2; ++_i) \
;         __builtin_amdgcn_global_load_lds((const unsigned*)((const char*)(gbase) + (RR)[_i] * (ld) + C2[_i]), (LAS unsigned*)(lds + (bufoff) + ldsw + _i * 8192), 16, 0, 0); } while (0)
; #define PG8_LDA(dst, b, h) do { _Pragma("unroll") for (int m = 0; m < 4; ++m) _Pragma("unroll") for (int k = 0; k < 2; ++k) dst[m][k] = *(const LAS bf16x8*)(lds + PG8_SA(b, h) + aoff + m * 2048 + k * 1024); } while (0)
; #define PG8_LDB(dst, b, h) do { _Pragma("unroll") for (int n = 0; n < 2; ++n) _Pragma("unroll") for (int k = 0; k < 2; ++k) dst[n][k] = *(const LAS bf16x8*)(lds + PG8_SB(b, h) + boff + n * 2048 + k * 1024); } while (0)
; #define PG8_MMA(ai, bj, At, Bt) do { __builtin_amdgcn_s_setprio(1); _Pragma("unroll") for (int m = 0; m < 4; ++m) _Pragma("unroll") for (int n = 0; n < 2; ++n) _Pragma("unroll") for (int k = 0; k < 2; ++k) \
;         acc[ai][bj][m][n] = __builtin_amdgcn_mfma_f32_16x16x32_bf16(Bt[n][k], At[m][k], acc[ai][bj][m][n], 0, 0, 0); __builtin_amdgcn_s_setprio(0); } while (0)
; #define PG8_WAIT_V(n) asm volatile("s_waitcnt vmcnt(" #n ")" ::: "memory")
; #define PG8_WAIT_L(n) asm volatile("s_waitcnt lgkmcnt(" #n ")" ::: "memory")
; #define PG8_BAR __builtin_amdgcn_s_barrier()
; #define PG8_SCHED __builtin_amdgcn_sched_barrier(0)
; template <class Sched, class Epi>
; __device__ __forceinline__ void gemm_run(LAS unsigned char* lds, const Sched& S, const Epi& E) {
;     ...
;             PG8_LDB(B0, 0, 0); PG8_LDB(B1, 0, 1); PG8_SCHED; PG8_LDA(At, 0, 0); PG8_STAGE(PG8_SA(1, 1), a1 + (size_t)HALF * lda, RA, lda);
;             PG8_WAIT_V(8); PG8_WAIT_L(0); PG8_BAR; PG8_MMA(0, 0, At, B0); PG8_MMA(0, 1, At, B1); PG8_BAR; PG8_SCHED;
;             PG8_LDA(At, 0, 1); PG8_STAGE(PG8_SB(0, 0), b2, RB, lb2); PG8_STAGE(PG8_SB(0, 1), b2 + (size_t)HALF * lb2, RB, lb2); PG8_STAGE(PG8_SA(0, 0), a2, RA, la2);
;             PG8_WAIT_V(8); PG8_WAIT_L(0); PG8_BAR; PG8_MMA(1, 0, At, B0); PG8_MMA(1, 1, At, B1); PG8_BAR; PG8_SCHED;
.Lmad806_skip:
	s_add_i32 m0, s43, 0xc000
	ds_read_b128 v[172:175], v195
	ds_read_b128 v[176:179], v195 offset:1024
	ds_read_b128 v[180:183], v195 offset:2048
	ds_read_b128 v[196:199], v195 offset:3072
	ds_read_b128 v[200:203], v195 offset:4096
	ds_read_b128 v[204:207], v195 offset:5120
	ds_read_b128 v[208:211], v195 offset:6144
	ds_read_b128 v[212:215], v195 offset:7168
	global_load_lds_dwordx4 v224, s[98:99]
	s_add_i32 m0, s43, 0xe000
	s_nop 0
	global_load_lds_dwordx4 v226, s[98:99]
	s_waitcnt vmcnt(8)
	s_waitcnt lgkmcnt(0)
	s_barrier
	s_waitcnt lgkmcnt(0)
	v_mfma_f32_16x16x32_bf16 v[126:129], v[134:137], v[172:175], v[126:129]
	v_mfma_f32_16x16x32_bf16 v[118:121], v[142:145], v[172:175], v[118:121]
	v_mfma_f32_16x16x32_bf16 v[110:113], v[134:137], v[180:183], v[110:113]
	v_mfma_f32_16x16x32_bf16 v[102:105], v[142:145], v[180:183], v[102:105]
	v_mfma_f32_16x16x32_bf16 v[94:97], v[134:137], v[200:203], v[94:97]
	v_mfma_f32_16x16x32_bf16 v[86:89], v[142:145], v[200:203], v[86:89]
	v_mfma_f32_16x16x32_bf16 v[78:81], v[134:137], v[208:211], v[78:81]
	v_mfma_f32_16x16x32_bf16 v[70:73], v[142:145], v[208:211], v[70:73]
	v_mfma_f32_16x16x32_bf16 v[126:129], v[138:141], v[176:179], v[126:129]
	v_mfma_f32_16x16x32_bf16 v[118:121], v[152:155], v[176:179], v[118:121]
	v_mfma_f32_16x16x32_bf16 v[110:113], v[138:141], v[196:199], v[110:113]
	v_mfma_f32_16x16x32_bf16 v[102:105], v[152:155], v[196:199], v[102:105]
	v_mfma_f32_16x16x32_bf16 v[94:97], v[138:141], v[204:207], v[94:97]
	v_mfma_f32_16x16x32_bf16 v[86:89], v[152:155], v[204:207], v[86:89]
	v_mfma_f32_16x16x32_bf16 v[78:81], v[138:141], v[212:215], v[78:81]
	v_mfma_f32_16x16x32_bf16 v[70:73], v[152:155], v[212:215], v[70:73]
	v_mfma_f32_16x16x32_bf16 v[122:125], v[156:159], v[172:175], v[122:125]
	v_mfma_f32_16x16x32_bf16 v[114:117], v[164:167], v[172:175], v[114:117]
	v_mfma_f32_16x16x32_bf16 v[106:109], v[156:159], v[180:183], v[106:109]
	v_mfma_f32_16x16x32_bf16 v[98:101], v[164:167], v[180:183], v[98:101]
	v_mfma_f32_16x16x32_bf16 v[90:93], v[156:159], v[200:203], v[90:93]
	v_mfma_f32_16x16x32_bf16 v[82:85], v[164:167], v[200:203], v[82:85]
	v_mfma_f32_16x16x32_bf16 v[74:77], v[156:159], v[208:211], v[74:77]
	v_mfma_f32_16x16x32_bf16 v[66:69], v[164:167], v[208:211], v[66:69]
	v_mfma_f32_16x16x32_bf16 v[122:125], v[160:163], v[176:179], v[122:125]
	v_mfma_f32_16x16x32_bf16 v[114:117], v[168:171], v[176:179], v[114:117]
	v_mfma_f32_16x16x32_bf16 v[106:109], v[160:163], v[196:199], v[106:109]
	v_mfma_f32_16x16x32_bf16 v[98:101], v[168:171], v[196:199], v[98:101]
	v_mfma_f32_16x16x32_bf16 v[90:93], v[160:163], v[204:207], v[90:93]
	v_mfma_f32_16x16x32_bf16 v[82:85], v[168:171], v[204:207], v[82:85]
	v_mfma_f32_16x16x32_bf16 v[74:77], v[160:163], v[212:215], v[74:77]
	v_mfma_f32_16x16x32_bf16 v[66:69], v[168:171], v[212:215], v[66:69]
	s_barrier
	s_add_i32 s50, s74, s3
	s_mov_b32 m0, s50
	ds_read_b128 v[172:175], v195 offset:16384
	ds_read_b128 v[176:179], v195 offset:17408
	ds_read_b128 v[180:183], v195 offset:18432
	ds_read_b128 v[196:199], v195 offset:19456
	ds_read_b128 v[200:203], v195 offset:20480
	ds_read_b128 v[204:207], v195 offset:21504
	ds_read_b128 v[208:211], v195 offset:22528
	ds_read_b128 v[212:215], v195 offset:23552
	global_load_lds_dwordx4 v216, s[48:49]
	s_add_i32 m0, s50, 0x2000
	s_lshl_b64 s[50:51], s[6:7], 7
	s_mov_b64 s[98:99], s[48:49]
	s_add_u32 s48, s48, s50
	s_addc_u32 s49, s49, s51
	s_mov_b64 s[100:101], s[48:49]
	s_add_i32 s6, s75, s3
	global_load_lds_dwordx4 v218, s[98:99]
	s_mov_b32 m0, s6
	global_load_lds_dwordx4 v216, s[48:49]
	s_add_i32 m0, s6, 0x2000
	global_load_lds_dwordx4 v218, s[48:49]
	s_mov_b32 m0, s43
	s_nop 0
	global_load_lds_dwordx4 v220, s[60:61]
	s_mov_b32 m0, s65
	s_nop 0
	global_load_lds_dwordx4 v222, s[60:61]
	s_waitcnt vmcnt(8)
	s_waitcnt lgkmcnt(0)
	s_barrier
	s_waitcnt lgkmcnt(0)
	v_mfma_f32_16x16x32_bf16 v[62:65], v[134:137], v[172:175], v[62:65]
	v_mfma_f32_16x16x32_bf16 v[54:57], v[142:145], v[172:175], v[54:57]
	v_mfma_f32_16x16x32_bf16 v[46:49], v[134:137], v[180:183], v[46:49]
	v_mfma_f32_16x16x32_bf16 v[38:41], v[142:145], v[180:183], v[38:41]
	v_mfma_f32_16x16x32_bf16 v[30:33], v[134:137], v[200:203], v[30:33]
	v_mfma_f32_16x16x32_bf16 v[22:25], v[142:145], v[200:203], v[22:25]
	v_mfma_f32_16x16x32_bf16 v[14:17], v[134:137], v[208:211], v[14:17]
	v_mfma_f32_16x16x32_bf16 v[6:9], v[142:145], v[208:211], v[6:9]
	v_mfma_f32_16x16x32_bf16 v[62:65], v[138:141], v[176:179], v[62:65]
	v_mfma_f32_16x16x32_bf16 v[54:57], v[152:155], v[176:179], v[54:57]
	v_mfma_f32_16x16x32_bf16 v[46:49], v[138:141], v[196:199], v[46:49]
	v_mfma_f32_16x16x32_bf16 v[38:41], v[152:155], v[196:199], v[38:41]
	v_mfma_f32_16x16x32_bf16 v[30:33], v[138:141], v[204:207], v[30:33]
	v_mfma_f32_16x16x32_bf16 v[22:25], v[152:155], v[204:207], v[22:25]
	v_mfma_f32_16x16x32_bf16 v[14:17], v[138:141], v[212:215], v[14:17]
	v_mfma_f32_16x16x32_bf16 v[6:9], v[152:155], v[212:215], v[6:9]
	v_mfma_f32_16x16x32_bf16 v[58:61], v[156:159], v[172:175], v[58:61]
	v_mfma_f32_16x16x32_bf16 v[50:53], v[164:167], v[172:175], v[50:53]
	v_mfma_f32_16x16x32_bf16 v[42:45], v[156:159], v[180:183], v[42:45]
	v_mfma_f32_16x16x32_bf16 v[34:37], v[164:167], v[180:183], v[34:37]
	v_mfma_f32_16x16x32_bf16 v[26:29], v[156:159], v[200:203], v[26:29]
	v_mfma_f32_16x16x32_bf16 v[18:21], v[164:167], v[200:203], v[18:21]
	v_mfma_f32_16x16x32_bf16 v[10:13], v[156:159], v[208:211], v[10:13]
	v_mfma_f32_16x16x32_bf16 v[2:5], v[164:167], v[208:211], v[2:5]
	v_mfma_f32_16x16x32_bf16 v[58:61], v[160:163], v[176:179], v[58:61]
	v_mfma_f32_16x16x32_bf16 v[50:53], v[168:171], v[176:179], v[50:53]
	v_mfma_f32_16x16x32_bf16 v[42:45], v[160:163], v[196:199], v[42:45]
	v_mfma_f32_16x16x32_bf16 v[34:37], v[168:171], v[196:199], v[34:37]
	v_mfma_f32_16x16x32_bf16 v[26:29], v[160:163], v[204:207], v[26:29]
	v_mfma_f32_16x16x32_bf16 v[18:21], v[168:171], v[204:207], v[18:21]
	v_mfma_f32_16x16x32_bf16 v[10:13], v[160:163], v[212:215], v[10:13]
	v_mfma_f32_16x16x32_bf16 v[2:5], v[168:171], v[212:215], v[2:5]
	s_barrier
; #define PG8_STAGE(bufoff, gbase, RR, ld) do { _Pragma("unroll") for (int _i = 0; _i < 2; ++_i) \
;         __builtin_amdgcn_global_load_lds((const unsigned*)((const char*)(gbase) + (RR)[_i] * (ld) + C2[_i]), (LAS unsigned*)(lds + (bufoff) + ldsw + _i * 8192), 16, 0, 0); } while (0)
; #define PG8_LDA(dst, b, h) do { _Pragma("unroll") for (int m = 0; m < 4; ++m) _Pragma("unroll") for (int k = 0; k < 2; ++k) dst[m][k] = *(const LAS bf16x8*)(lds + PG8_SA(b, h) + aoff + m * 2048 + k * 1024); } while (0)
; #define PG8_LDB(dst, b, h) do { _Pragma("unroll") for (int n = 0; n < 2; ++n) _Pragma("unroll") for (int k = 0; k < 2; ++k) dst[n][k] = *(const LAS bf16x8*)(lds + PG8_SB(b, h) + boff + n * 2048 + k * 1024); } while (0)
; #define PG8_MMA(ai, bj, At, Bt) do { __builtin_amdgcn_s_setprio(1); _Pragma("unroll") for (int m = 0; m < 4; ++m) _Pragma("unroll") for (int n = 0; n < 2; ++n) _Pragma("unroll") for (int k = 0; k < 2; ++k) \
;         acc[ai][bj][m][n] = __builtin_amdgcn_mfma_f32_16x16x32_bf16(Bt[n][k], At[m][k], acc[ai][bj][m][n], 0, 0, 0); __builtin_amdgcn_s_setprio(0); } while (0)
; #define PG8_WAIT_V(n) asm volatile("s_waitcnt vmcnt(" #n ")" ::: "memory")
; #define PG8_WAIT_L(n) asm volatile("s_waitcnt lgkmcnt(" #n ")" ::: "memory")
; #define PG8_BAR __builtin_amdgcn_s_barrier()
; #define PG8_SCHED __builtin_amdgcn_sched_barrier(0)
; template <class Sched, class Epi>
; __device__ __forceinline__ void gemm_run(LAS unsigned char* lds, const Sched& S, const Epi& E) {
;     ...
;             PG8_LDB(B0, 1, 0); PG8_LDB(B1, 1, 1); PG8_SCHED; PG8_LDA(At, 1, 0); PG8_STAGE(PG8_SA(0, 1), a2 + (size_t)HALF * la2, RA, la2);
;             PG8_WAIT_V(8); PG8_WAIT_L(0); PG8_BAR; PG8_MMA(0, 0, At, B0); PG8_MMA(0, 1, At, B1); PG8_BAR; PG8_SCHED;
;             PG8_LDA(At, 1, 1); PG8_STAGE(PG8_SB(1, 0), b3, RB, lb2); PG8_STAGE(PG8_SB(1, 1), b3 + (size_t)HALF * lb2, RB, lb2); PG8_STAGE(PG8_SA(1, 0), a3, RA, la2);
;             PG8_WAIT_V(8); PG8_WAIT_L(0); PG8_BAR; PG8_MMA(1, 0, At, B0); PG8_MMA(1, 1, At, B1); PG8_BAR; PG8_SCHED;
;         }
;         if (wr == 0) PG8_BAR;
;         if constexpr (!Epi::AFTER_DRAIN) E(acc, cur, wr, wc, fr, fq);
;         if (!has_next) break;
	s_add_i32 s6, 0, 0x18000
	s_add_i32 s50, 0, 0x1c000
	ds_read_b128 v[134:137], v193 offset:32768
	ds_read_b128 v[138:141], v193 offset:33792
	ds_read_b128 v[142:145], v193 offset:34816
	ds_read_b128 v[152:155], v193 offset:35840
	ds_read_b128 v[156:159], v194 offset:32768
	ds_read_b128 v[160:163], v194 offset:33792
	ds_read_b128 v[164:167], v194 offset:34816
	ds_read_b128 v[168:171], v194 offset:35840
	s_mov_b32 s63, s7
	s_lshl_b64 s[48:49], s[62:63], 7
	s_add_u32 s48, s60, s48
	s_addc_u32 s49, s61, s49
	s_mov_b32 m0, s66
	ds_read_b128 v[172:175], v195 offset:32768
	ds_read_b128 v[176:179], v195 offset:33792
	ds_read_b128 v[180:183], v195 offset:34816
	ds_read_b128 v[196:199], v195 offset:35840
	ds_read_b128 v[200:203], v195 offset:36864
	ds_read_b128 v[204:207], v195 offset:37888
	ds_read_b128 v[208:211], v195 offset:38912
	ds_read_b128 v[212:215], v195 offset:39936
	global_load_lds_dwordx4 v220, s[48:49]
	s_mov_b32 m0, s67
	s_nop 0
	global_load_lds_dwordx4 v222, s[48:49]
	s_waitcnt vmcnt(8)
	s_waitcnt lgkmcnt(0)
	s_barrier
	s_waitcnt lgkmcnt(0)
	v_mfma_f32_16x16x32_bf16 v[126:129], v[134:137], v[172:175], v[126:129]
	v_mfma_f32_16x16x32_bf16 v[118:121], v[142:145], v[172:175], v[118:121]
	v_mfma_f32_16x16x32_bf16 v[110:113], v[134:137], v[180:183], v[110:113]
	v_mfma_f32_16x16x32_bf16 v[102:105], v[142:145], v[180:183], v[102:105]
	v_mfma_f32_16x16x32_bf16 v[94:97], v[134:137], v[200:203], v[94:97]
	v_mfma_f32_16x16x32_bf16 v[86:89], v[142:145], v[200:203], v[86:89]
	v_mfma_f32_16x16x32_bf16 v[78:81], v[134:137], v[208:211], v[78:81]
	v_mfma_f32_16x16x32_bf16 v[70:73], v[142:145], v[208:211], v[70:73]
	v_mfma_f32_16x16x32_bf16 v[126:129], v[138:141], v[176:179], v[126:129]
	v_mfma_f32_16x16x32_bf16 v[118:121], v[152:155], v[176:179], v[118:121]
	v_mfma_f32_16x16x32_bf16 v[110:113], v[138:141], v[196:199], v[110:113]
	v_mfma_f32_16x16x32_bf16 v[102:105], v[152:155], v[196:199], v[102:105]
	v_mfma_f32_16x16x32_bf16 v[94:97], v[138:141], v[204:207], v[94:97]
	v_mfma_f32_16x16x32_bf16 v[86:89], v[152:155], v[204:207], v[86:89]
	v_mfma_f32_16x16x32_bf16 v[78:81], v[138:141], v[212:215], v[78:81]
	v_mfma_f32_16x16x32_bf16 v[70:73], v[152:155], v[212:215], v[70:73]
	v_mfma_f32_16x16x32_bf16 v[122:125], v[156:159], v[172:175], v[122:125]
	v_mfma_f32_16x16x32_bf16 v[114:117], v[164:167], v[172:175], v[114:117]
	v_mfma_f32_16x16x32_bf16 v[106:109], v[156:159], v[180:183], v[106:109]
	v_mfma_f32_16x16x32_bf16 v[98:101], v[164:167], v[180:183], v[98:101]
	v_mfma_f32_16x16x32_bf16 v[90:93], v[156:159], v[200:203], v[90:93]
	v_mfma_f32_16x16x32_bf16 v[82:85], v[164:167], v[200:203], v[82:85]
	v_mfma_f32_16x16x32_bf16 v[74:77], v[156:159], v[208:211], v[74:77]
	v_mfma_f32_16x16x32_bf16 v[66:69], v[164:167], v[208:211], v[66:69]
	v_mfma_f32_16x16x32_bf16 v[122:125], v[160:163], v[176:179], v[122:125]
	v_mfma_f32_16x16x32_bf16 v[114:117], v[168:171], v[176:179], v[114:117]
	v_mfma_f32_16x16x32_bf16 v[106:109], v[160:163], v[196:199], v[106:109]
	v_mfma_f32_16x16x32_bf16 v[98:101], v[168:171], v[196:199], v[98:101]
	v_mfma_f32_16x16x32_bf16 v[90:93], v[160:163], v[204:207], v[90:93]
	v_mfma_f32_16x16x32_bf16 v[82:85], v[168:171], v[204:207], v[82:85]
	v_mfma_f32_16x16x32_bf16 v[74:77], v[160:163], v[212:215], v[74:77]
	v_mfma_f32_16x16x32_bf16 v[66:69], v[168:171], v[212:215], v[66:69]
	s_barrier
	s_add_i32 s6, s6, s3
	s_add_u32 s98, s98, 0x80
	s_addc_u32 s99, s99, 0
	s_mov_b32 m0, s6
	ds_read_b128 v[172:175], v195 offset:49152
	ds_read_b128 v[176:179], v195 offset:50176
	ds_read_b128 v[180:183], v195 offset:51200
	ds_read_b128 v[196:199], v195 offset:52224
	ds_read_b128 v[200:203], v195 offset:53248
	ds_read_b128 v[204:207], v195 offset:54272
	ds_read_b128 v[208:211], v195 offset:55296
	ds_read_b128 v[212:215], v195 offset:56320
	global_load_lds_dwordx4 v216, s[98:99]
	s_add_i32 m0, s6, 0x2000
	s_add_i32 s6, s50, s3
	global_load_lds_dwordx4 v218, s[98:99]
	s_add_u32 s100, s100, 0x80
	s_addc_u32 s101, s101, 0
	s_mov_b32 m0, s6
	s_nop 0
	global_load_lds_dwordx4 v216, s[100:101]
	s_add_i32 m0, s6, 0x2000
	s_nop 0
	global_load_lds_dwordx4 v218, s[100:101]
	s_add_u32 s48, s60, 0x80
	s_addc_u32 s49, s61, 0
	s_mov_b32 m0, s68
	s_nop 0
	global_load_lds_dwordx4 v220, s[48:49]
	s_mov_b32 m0, s69
	s_nop 0
	global_load_lds_dwordx4 v222, s[48:49]
	s_waitcnt vmcnt(8)
	s_waitcnt lgkmcnt(0)
	s_barrier
	s_waitcnt lgkmcnt(0)
	v_mfma_f32_16x16x32_bf16 v[62:65], v[134:137], v[172:175], v[62:65]
	v_mfma_f32_16x16x32_bf16 v[54:57], v[142:145], v[172:175], v[54:57]
	v_mfma_f32_16x16x32_bf16 v[46:49], v[134:137], v[180:183], v[46:49]
	v_mfma_f32_16x16x32_bf16 v[38:41], v[142:145], v[180:183], v[38:41]
	v_mfma_f32_16x16x32_bf16 v[30:33], v[134:137], v[200:203], v[30:33]
	v_mfma_f32_16x16x32_bf16 v[22:25], v[142:145], v[200:203], v[22:25]
	v_mfma_f32_16x16x32_bf16 v[14:17], v[134:137], v[208:211], v[14:17]
	v_mfma_f32_16x16x32_bf16 v[6:9], v[142:145], v[208:211], v[6:9]
	v_mfma_f32_16x16x32_bf16 v[62:65], v[138:141], v[176:179], v[62:65]
	v_mfma_f32_16x16x32_bf16 v[54:57], v[152:155], v[176:179], v[54:57]
	v_mfma_f32_16x16x32_bf16 v[46:49], v[138:141], v[196:199], v[46:49]
	v_mfma_f32_16x16x32_bf16 v[38:41], v[152:155], v[196:199], v[38:41]
	v_mfma_f32_16x16x32_bf16 v[30:33], v[138:141], v[204:207], v[30:33]
	v_mfma_f32_16x16x32_bf16 v[22:25], v[152:155], v[204:207], v[22:25]
	v_mfma_f32_16x16x32_bf16 v[14:17], v[138:141], v[212:215], v[14:17]
	v_mfma_f32_16x16x32_bf16 v[6:9], v[152:155], v[212:215], v[6:9]
	v_mfma_f32_16x16x32_bf16 v[58:61], v[156:159], v[172:175], v[58:61]
	v_mfma_f32_16x16x32_bf16 v[50:53], v[164:167], v[172:175], v[50:53]
	v_mfma_f32_16x16x32_bf16 v[42:45], v[156:159], v[180:183], v[42:45]
	v_mfma_f32_16x16x32_bf16 v[34:37], v[164:167], v[180:183], v[34:37]
	v_mfma_f32_16x16x32_bf16 v[26:29], v[156:159], v[200:203], v[26:29]
	v_mfma_f32_16x16x32_bf16 v[18:21], v[164:167], v[200:203], v[18:21]
	v_mfma_f32_16x16x32_bf16 v[10:13], v[156:159], v[208:211], v[10:13]
	v_mfma_f32_16x16x32_bf16 v[2:5], v[164:167], v[208:211], v[2:5]
	v_mfma_f32_16x16x32_bf16 v[58:61], v[160:163], v[176:179], v[58:61]
	v_mfma_f32_16x16x32_bf16 v[50:53], v[168:171], v[176:179], v[50:53]
	v_mfma_f32_16x16x32_bf16 v[42:45], v[160:163], v[196:199], v[42:45]
	v_mfma_f32_16x16x32_bf16 v[34:37], v[168:171], v[196:199], v[34:37]
	v_mfma_f32_16x16x32_bf16 v[26:29], v[160:163], v[204:207], v[26:29]
	v_mfma_f32_16x16x32_bf16 v[18:21], v[168:171], v[204:207], v[18:21]
	v_mfma_f32_16x16x32_bf16 v[10:13], v[160:163], v[212:215], v[10:13]
	v_mfma_f32_16x16x32_bf16 v[2:5], v[168:171], v[212:215], v[2:5]
	s_barrier
	s_add_u32 s58, s58, 0x100
	s_addc_u32 s59, s59, 0
	s_cmp_ge_i32 s47, s81
	s_mov_b32 s6, s47
	s_cbranch_scc0 .LBB0_806
	s_and_b64 vcc, exec, s[10:11]
	s_cbranch_vccz .LBB0_809
	s_barrier
